# final RMSNorm rows dealt to the owning XCD: seam 17 XCD-local (12 local seams, 4 rendezvous-only, 2 full)
# speedup vs baseline: 1.0429x; 1.0053x over previous
; __device__ __forceinline__ unsigned xb_ld(unsigned* p)              { return __hip_atomic_load(p, __ATOMIC_RELAXED, __HIP_MEMORY_SCOPE_AGENT); }
; __device__ __forceinline__ unsigned xb_add(unsigned* p, unsigned v) { return __hip_atomic_fetch_add(p, v, __ATOMIC_RELAXED, __HIP_MEMORY_SCOPE_AGENT); }
; #define XB_SPIN(cond, bar) do { unsigned _sp = 0; while (cond) { __builtin_amdgcn_s_sleep(1); \
;     if ((++_sp & 255u) == 0u) { if (xb_ld(&(bar)[XB_TMO])) break; if (_sp > XB_SPIN_CAP) { atomicAdd(&(bar)[XB_TMO], 1u); break; } } } } while (0)
; __device__ __forceinline__ void xcd_barrier(const XcdBarrier& b) {
;     ...
;         const unsigned old = xb_add(&bar[XB_XSUB(b.x)], 1u);
;         const unsigned gen = old / nloc;
;         if (old + 1u == (gen + 1u) * nloc) {
;             __builtin_amdgcn_fence(__ATOMIC_RELEASE, "agent");
;             asm volatile("s_waitcnt vmcnt(0)" ::: "memory");
;             const unsigned og = xb_add(&bar[XB_TOP], 1u);
;             const unsigned tg = og / nx;
;             if (og + 1u == (tg + 1u) * nx) xb_add(&bar[XB_TOPGEN], 1u);
;             else XB_SPIN(xb_ld(&bar[XB_TOPGEN]) == tg, bar);
;             __builtin_amdgcn_fence(__ATOMIC_ACQUIRE, "agent");
;             xb_add(&bar[XB_XGEN(b.x)], 1u);
;             asm volatile("s_waitcnt vmcnt(0)" ::: "memory");
.LBB0_264:
	s_andn2_saveexec_b64 s[8:9], s[8:9]
	s_cbranch_execz .LBB0_284
	s_mov_b64 s[8:9], exec
	v_readlane_b32 s101, v249, 48
	s_nop 3
	s_cmp_lg_u32 s101, 0
	s_cbranch_scc1 .LBB0_281
	buffer_wbl2 sc1
	s_waitcnt lgkmcnt(0)
	s_waitcnt vmcnt(0)
	v_mbcnt_lo_u32_b32 v1, s8, 0
	v_mbcnt_hi_u32_b32 v1, s9, v1
	v_cmp_eq_u32_e32 vcc, 0, v1
	s_and_saveexec_b64 s[10:11], vcc
	s_cbranch_execz .LBB0_267
	s_bcnt1_i32_b64 s3, s[8:9]
	v_mov_b32_e32 v2, 0x183000
	v_mov_b32_e32 v3, s3
	global_atomic_add v2, v2, v3, s[28:29] offset:1024 sc0

; __device__ __forceinline__ unsigned xb_ld(unsigned* p)              { return __hip_atomic_load(p, __ATOMIC_RELAXED, __HIP_MEMORY_SCOPE_AGENT); }
; __device__ __forceinline__ unsigned xb_add(unsigned* p, unsigned v) { return __hip_atomic_fetch_add(p, v, __ATOMIC_RELAXED, __HIP_MEMORY_SCOPE_AGENT); }
; #define XB_SPIN(cond, bar) do { unsigned _sp = 0; while (cond) { __builtin_amdgcn_s_sleep(1); \
;     if ((++_sp & 255u) == 0u) { if (xb_ld(&(bar)[XB_TMO])) break; if (_sp > XB_SPIN_CAP) { atomicAdd(&(bar)[XB_TMO], 1u); break; } } } } while (0)
; __device__ __forceinline__ void xcd_barrier(const XcdBarrier& b) {
;     ...
;         const unsigned old = xb_add(&bar[XB_XSUB(b.x)], 1u);
;         const unsigned gen = old / nloc;
;         if (old + 1u == (gen + 1u) * nloc) {
;             __builtin_amdgcn_fence(__ATOMIC_RELEASE, "agent");
;             asm volatile("s_waitcnt vmcnt(0)" ::: "memory");
;             const unsigned og = xb_add(&bar[XB_TOP], 1u);
;             const unsigned tg = og / nx;
;             if (og + 1u == (tg + 1u) * nx) xb_add(&bar[XB_TOPGEN], 1u);
;             else XB_SPIN(xb_ld(&bar[XB_TOPGEN]) == tg, bar);
;             __builtin_amdgcn_fence(__ATOMIC_ACQUIRE, "agent");
;             xb_add(&bar[XB_XGEN(b.x)], 1u);
;             asm volatile("s_waitcnt vmcnt(0)" ::: "memory");
.LBB0_365:
	s_andn2_saveexec_b64 s[8:9], s[8:9]
	s_cbranch_execz .LBB0_385
	s_mov_b64 s[8:9], exec
	v_readlane_b32 s101, v249, 48
	s_nop 3
	s_cmp_lg_u32 s101, 0
	s_cbranch_scc1 .Lnowb_0
	buffer_wbl2 sc1

; __device__ __forceinline__ unsigned xb_ld(unsigned* p)              { return __hip_atomic_load(p, __ATOMIC_RELAXED, __HIP_MEMORY_SCOPE_AGENT); }
; __device__ __forceinline__ unsigned xb_add(unsigned* p, unsigned v) { return __hip_atomic_fetch_add(p, v, __ATOMIC_RELAXED, __HIP_MEMORY_SCOPE_AGENT); }
; #define XB_SPIN(cond, bar) do { unsigned _sp = 0; while (cond) { __builtin_amdgcn_s_sleep(1); \
;     if ((++_sp & 255u) == 0u) { if (xb_ld(&(bar)[XB_TMO])) break; if (_sp > XB_SPIN_CAP) { atomicAdd(&(bar)[XB_TMO], 1u); break; } } } } while (0)
; __device__ __forceinline__ void xcd_barrier(const XcdBarrier& b) {
;     ...
;         const unsigned old = xb_add(&bar[XB_XSUB(b.x)], 1u);
;         const unsigned gen = old / nloc;
;         if (old + 1u == (gen + 1u) * nloc) {
;             __builtin_amdgcn_fence(__ATOMIC_RELEASE, "agent");
;             asm volatile("s_waitcnt vmcnt(0)" ::: "memory");
;             const unsigned og = xb_add(&bar[XB_TOP], 1u);
;             const unsigned tg = og / nx;
;             if (og + 1u == (tg + 1u) * nx) xb_add(&bar[XB_TOPGEN], 1u);
;             else XB_SPIN(xb_ld(&bar[XB_TOPGEN]) == tg, bar);
;             __builtin_amdgcn_fence(__ATOMIC_ACQUIRE, "agent");
;             xb_add(&bar[XB_XGEN(b.x)], 1u);
;             asm volatile("s_waitcnt vmcnt(0)" ::: "memory");
.LBB0_523:
	s_andn2_saveexec_b64 s[10:11], s[10:11]
	s_cbranch_execz .LBB0_543
	s_mov_b64 s[10:11], exec
	v_readlane_b32 s101, v249, 48
	s_nop 3
	s_cmp_lg_u32 s101, 0
	s_cbranch_scc1 .LBB0_540
	buffer_wbl2 sc1
	s_waitcnt lgkmcnt(0)
	s_waitcnt vmcnt(0)
	v_mbcnt_lo_u32_b32 v1, s10, 0
	v_mbcnt_hi_u32_b32 v1, s11, v1
	v_cmp_eq_u32_e32 vcc, 0, v1
	s_and_saveexec_b64 s[12:13], vcc
	s_cbranch_execz .LBB0_526
	s_bcnt1_i32_b64 s3, s[10:11]
	v_mov_b32_e32 v2, 0x183000
	v_mov_b32_e32 v3, s3
	global_atomic_add v2, v2, v3, s[28:29] offset:1024 sc0

; __device__ __forceinline__ unsigned xb_ld(unsigned* p)              { return __hip_atomic_load(p, __ATOMIC_RELAXED, __HIP_MEMORY_SCOPE_AGENT); }
; __device__ __forceinline__ unsigned xb_add(unsigned* p, unsigned v) { return __hip_atomic_fetch_add(p, v, __ATOMIC_RELAXED, __HIP_MEMORY_SCOPE_AGENT); }
; #define XB_SPIN(cond, bar) do { unsigned _sp = 0; while (cond) { __builtin_amdgcn_s_sleep(1); \
;     if ((++_sp & 255u) == 0u) { if (xb_ld(&(bar)[XB_TMO])) break; if (_sp > XB_SPIN_CAP) { atomicAdd(&(bar)[XB_TMO], 1u); break; } } } } while (0)
; __device__ __forceinline__ void xcd_barrier(const XcdBarrier& b) {
;     ...
;         const unsigned old = xb_add(&bar[XB_XSUB(b.x)], 1u);
;         const unsigned gen = old / nloc;
;         if (old + 1u == (gen + 1u) * nloc) {
;             __builtin_amdgcn_fence(__ATOMIC_RELEASE, "agent");
;             asm volatile("s_waitcnt vmcnt(0)" ::: "memory");
;             const unsigned og = xb_add(&bar[XB_TOP], 1u);
;             const unsigned tg = og / nx;
;             if (og + 1u == (tg + 1u) * nx) xb_add(&bar[XB_TOPGEN], 1u);
;             else XB_SPIN(xb_ld(&bar[XB_TOPGEN]) == tg, bar);
;             __builtin_amdgcn_fence(__ATOMIC_ACQUIRE, "agent");
;             xb_add(&bar[XB_XGEN(b.x)], 1u);
;             asm volatile("s_waitcnt vmcnt(0)" ::: "memory");
.LBB0_1486:
	s_andn2_saveexec_b64 s[6:7], s[6:7]
	s_cbranch_execz .LBB0_1506
	s_mov_b64 s[6:7], exec
	v_readlane_b32 s101, v249, 48
	s_nop 3
	s_cmp_lg_u32 s101, 0
	s_cbranch_scc1 .LBB0_1503
	buffer_wbl2 sc1
	s_waitcnt lgkmcnt(0)
	s_waitcnt vmcnt(0)
	v_mbcnt_lo_u32_b32 v1, s6, 0
	v_mbcnt_hi_u32_b32 v1, s7, v1
	v_cmp_eq_u32_e32 vcc, 0, v1
	s_and_saveexec_b64 s[8:9], vcc
	s_cbranch_execz .LBB0_1489
	s_bcnt1_i32_b64 s3, s[6:7]
	v_mov_b32_e32 v2, 0x183000
	v_mov_b32_e32 v3, s3
	global_atomic_add v2, v2, v3, s[28:29] offset:1024 sc0

; __device__ __forceinline__ unsigned xb_ld(unsigned* p)              { return __hip_atomic_load(p, __ATOMIC_RELAXED, __HIP_MEMORY_SCOPE_AGENT); }
; __device__ __forceinline__ unsigned xb_add(unsigned* p, unsigned v) { return __hip_atomic_fetch_add(p, v, __ATOMIC_RELAXED, __HIP_MEMORY_SCOPE_AGENT); }
; #define XB_SPIN(cond, bar) do { unsigned _sp = 0; while (cond) { __builtin_amdgcn_s_sleep(1); \
;     if ((++_sp & 255u) == 0u) { if (xb_ld(&(bar)[XB_TMO])) break; if (_sp > XB_SPIN_CAP) { atomicAdd(&(bar)[XB_TMO], 1u); break; } } } } while (0)
; __device__ __forceinline__ void xcd_barrier(const XcdBarrier& b) {
;     ...
;         const unsigned old = xb_add(&bar[XB_XSUB(b.x)], 1u);
;         const unsigned gen = old / nloc;
;         if (old + 1u == (gen + 1u) * nloc) {
;             __builtin_amdgcn_fence(__ATOMIC_RELEASE, "agent");
;             asm volatile("s_waitcnt vmcnt(0)" ::: "memory");
;             const unsigned og = xb_add(&bar[XB_TOP], 1u);
;             const unsigned tg = og / nx;
;             if (og + 1u == (tg + 1u) * nx) xb_add(&bar[XB_TOPGEN], 1u);
;             else XB_SPIN(xb_ld(&bar[XB_TOPGEN]) == tg, bar);
;             __builtin_amdgcn_fence(__ATOMIC_ACQUIRE, "agent");
;             xb_add(&bar[XB_XGEN(b.x)], 1u);
;             asm volatile("s_waitcnt vmcnt(0)" ::: "memory");
.LBB0_1881:
	s_andn2_saveexec_b64 s[6:7], s[6:7]
	s_cbranch_execz .LBB0_1901
	s_mov_b64 s[6:7], exec
	v_readlane_b32 s101, v249, 48
	s_nop 3
	s_cmp_lg_u32 s101, 0
	s_cbranch_scc1 .LBB0_1898
	buffer_wbl2 sc1
	s_waitcnt lgkmcnt(0)
	s_waitcnt vmcnt(0)
	v_mbcnt_lo_u32_b32 v1, s6, 0
	v_mbcnt_hi_u32_b32 v1, s7, v1
	v_cmp_eq_u32_e32 vcc, 0, v1
	s_and_saveexec_b64 s[8:9], vcc
	s_cbranch_execz .LBB0_1884
	s_bcnt1_i32_b64 s6, s[6:7]
	v_mov_b32_e32 v2, 0x183000
	v_mov_b32_e32 v3, s6
	global_atomic_add v2, v2, v3, s[28:29] offset:1024 sc0

; __device__ __forceinline__ float rs_of(float ss) { return 1.0f / sqrtf(ss * (1.f / 1024.f) + 1e-6f); }
; __device__ __forceinline__ void final_rows(const bf16_t* XB, float* out, const float* g, const float* SS, int gw, int NGW, int lane) {
;     f32x4 gv[4];
; #pragma unroll
;     for (int j = 0; j < 4; ++j) gv[j] = ((const f32x4*)g)[lane + 64 * j];
;     for (int m0 = 4 * gw; m0 < T; m0 += 4 * NGW) {
;         u32x2 w[4][4]; float tp[4];
; #pragma unroll
;         for (int q = 0; q < 4; ++q) { const u32x2* xr = (const u32x2*)(XB + (size_t)(m0 + q) * D) + lane;
; #pragma unroll
;             for (int j = 0; j < 4; ++j) w[q][j] = xr[64 * j];
;             tp[q] = (lane < 16) ? SS[(size_t)lane * T + m0 + q] : 0.f; }
; #pragma unroll
;         for (int q = 0; q < 4; ++q) { float t = tp[q]; t += __shfl_xor(t, 1); t += __shfl_xor(t, 2); t += __shfl_xor(t, 4); t += __shfl_xor(t, 8); const float r = rs_of(__shfl(t, 0));
;             f32x4* o = (f32x4*)(out + (size_t)(m0 + q) * D) + lane;
; #pragma unroll
;             for (int j = 0; j < 4; ++j) o[64 * j] = (f32x4){bf_lo(w[q][j].x), bf_hi(w[q][j].x), bf_lo(w[q][j].y), bf_hi(w[q][j].y)} * r * gv[j]; } }
.LBB0_1902:
	s_cmp_lt_i32 s30, 19
	s_cselect_b64 s[2:3], -1, 0
	s_and_b64 s[0:1], s[2:3], s[0:1]
	s_andn2_b64 vcc, exec, s[0:1]
	s_cbranch_vccnz .LBB0_1914
	s_cmpk_gt_i32 s92, 0x1fff
	s_cbranch_scc1 .LBB0_1914
	v_lshlrev_b32_e32 v16, 4, v196
	s_waitcnt lgkmcnt(0)
	global_load_dwordx4 v[0:3], v16, s[24:25]
	global_load_dwordx4 v[4:7], v16, s[24:25] offset:1024
	global_load_dwordx4 v[8:11], v16, s[24:25] offset:2048
	global_load_dwordx4 v[12:15], v16, s[24:25] offset:3072
	v_mbcnt_lo_u32_b32 v18, -1, 0
	v_mbcnt_hi_u32_b32 v18, -1, v18
	v_and_b32_e32 v22, 64, v18
	v_xor_b32_e32 v19, 1, v18
	v_add_u32_e32 v22, 64, v22
	v_cmp_lt_i32_e32 vcc, v19, v22
	s_lshl_b32 s4, s92, 2
	s_ashr_i32 s5, s4, 31
	v_cndmask_b32_e32 v19, v18, v19, vcc
	v_lshlrev_b32_e32 v56, 2, v19
	v_xor_b32_e32 v19, 2, v18
	v_cmp_lt_i32_e32 vcc, v19, v22
	s_lshl_b32 s6, s22, 5
	v_readlane_b32 s98, v249, 48
	s_bfe_u32 s99, s92, 0x30003
	s_lshl_b32 s99, s99, 12
	s_lshr_b32 s100, s92, 6
	s_lshl_b32 s100, s100, 7
	s_or_b32 s99, s99, s100
	s_and_b32 s100, s92, 7
	s_lshl_b32 s100, s100, 2
	s_or_b32 s99, s99, s100
	s_cmp_lg_u32 s98, 0
	s_cselect_b32 s4, s99, s4
	s_cselect_b32 s6, 32, s6
	s_lshl_b64 s[2:3], s[4:5], 12
	v_cndmask_b32_e32 v19, v18, v19, vcc
	v_lshlrev_b32_e32 v57, 2, v19
	v_xor_b32_e32 v19, 4, v18
	v_cmp_lt_i32_e32 vcc, v19, v22
	s_add_u32 s2, s26, s2
	v_mov_b32_e32 v17, 0
	v_cndmask_b32_e32 v19, v18, v19, vcc
	v_lshlrev_b32_e32 v58, 2, v19
	v_xor_b32_e32 v19, 8, v18
	s_addc_u32 s3, s27, s3
	v_mov_b32_e32 v21, v17
	v_cmp_lt_i32_e32 vcc, v19, v22
	v_lshl_add_u64 v[16:17], s[2:3], 0, v[16:17]
	s_mov_b64 s[2:3], 0x3c00
	v_lshlrev_b32_e32 v20, 17, v196
	v_cndmask_b32_e32 v19, v18, v19, vcc
	v_lshlrev_b32_e32 v18, 2, v18
	v_lshl_add_u64 v[16:17], v[16:17], 0, s[2:3]
	s_ashr_i32 s7, s6, 31
	s_lshl_b64 s[2:3], s[4:5], 11
	v_cmp_gt_u32_e64 s[0:1], 16, v196
	v_lshlrev_b32_e32 v59, 2, v19
	v_and_b32_e32 v60, 0x100, v18
	s_lshl_b64 s[8:9], s[6:7], 12
	v_lshl_or_b32 v18, v196, 3, s2
	v_mov_b32_e32 v19, s3
	s_lshl_b64 s[10:11], s[6:7], 11
	v_lshl_add_u64 v[20:21], s[4:5], 2, v[20:21]
	s_lshl_b64 s[12:13], s[6:7], 2
	v_mov_b32_e32 v61, 0x358637bd
	s_mov_b32 s5, 0xf800000
	v_mov_b32_e32 v62, 0x260
	s_movk_i32 s7, 0xd000
	s_movk_i32 s14, 0xe000
	s_movk_i32 s15, 0xf000
	s_branch .LBB0_1906
.LBB0_1905:
	s_or_b64 exec, exec, s[2:3]
	s_waitcnt vmcnt(0)
	ds_bpermute_b32 v54, v56, v66
	v_lshlrev_b32_e32 v68, 16, v50
	v_and_b32_e32 v71, 0xffff0000, v51
	s_add_i32 s4, s4, s6
	v_lshl_add_u64 v[18:19], v[18:19], 0, s[10:11]
	s_waitcnt lgkmcnt(0)
	v_add_f32_e32 v54, v66, v54
	ds_bpermute_b32 v55, v57, v54
	s_bfe_u32 s99, s4, 0x20005
	s_cmp_lg_u32 s99, 0
	s_cselect_b32 s99, 1, 0
	s_cmp_lt_i32 s4, 0x8000
	s_cselect_b32 s100, 1, 0
	s_cmp_lg_u32 s98, 0
	s_cselect_b32 s99, s99, s100
	s_cmp_lg_u32 s99, 0
	v_lshl_add_u64 v[20:21], v[20:21], 0, s[12:13]
	s_waitcnt lgkmcnt(0)
	v_add_f32_e32 v54, v54, v55
	ds_bpermute_b32 v55, v58, v54
	s_waitcnt lgkmcnt(0)
	v_add_f32_e32 v66, v54, v55
	ds_bpermute_b32 v67, v59, v66
	v_lshlrev_b32_e32 v54, 16, v52
	v_and_b32_e32 v55, 0xffff0000, v52
	v_lshlrev_b32_e32 v52, 16, v53
	v_and_b32_e32 v53, 0xffff0000, v53
	s_waitcnt lgkmcnt(0)
	v_add_f32_e32 v66, v66, v67
	ds_bpermute_b32 v69, v60, v66
	v_add_co_u32_e32 v66, vcc, s7, v16
	s_waitcnt lgkmcnt(0)
	v_fmamk_f32 v69, v69, 0x3a800000, v61
	v_addc_co_u32_e32 v67, vcc, -1, v17, vcc
	v_mul_f32_e32 v70, 0x4f800000, v69
	v_cmp_gt_f32_e32 vcc, s5, v69
	s_nop 1
	v_cndmask_b32_e32 v72, v69, v70, vcc
	v_sqrt_f32_e32 v73, v72
	v_and_b32_e32 v69, 0xffff0000, v50
	v_lshlrev_b32_e32 v70, 16, v51
	v_add_u32_e32 v50, -1, v73
	v_add_u32_e32 v51, 1, v73
	v_fma_f32 v74, -v50, v73, v72
	v_fma_f32 v75, -v51, v73, v72
	v_cmp_ge_f32_e64 s[2:3], 0, v74
	s_nop 1
	v_cndmask_b32_e64 v50, v73, v50, s[2:3]
	v_cmp_lt_f32_e64 s[2:3], 0, v75
	ds_bpermute_b32 v73, v56, v65
	s_waitcnt lgkmcnt(0)
	v_add_f32_e32 v65, v65, v73
	v_cndmask_b32_e64 v50, v50, v51, s[2:3]
	v_mul_f32_e32 v51, 0x37800000, v50
	v_cndmask_b32_e32 v50, v50, v51, vcc
	v_cmp_class_f32_e32 vcc, v72, v62
	s_nop 1
	v_cndmask_b32_e32 v50, v50, v72, vcc
	v_div_scale_f32 v51, s[2:3], v50, v50, 1.0
	v_rcp_f32_e32 v72, v51
	v_div_scale_f32 v74, vcc, 1.0, v50, 1.0
	v_fma_f32 v75, -v51, v72, 1.0
	v_fmac_f32_e32 v72, v75, v72
	v_mul_f32_e32 v75, v74, v72
	v_fma_f32 v76, -v51, v75, v74
	v_fmac_f32_e32 v75, v76, v72
	v_fma_f32 v51, -v51, v75, v74
	v_div_fmas_f32 v51, v51, v72, v75
	v_div_fixup_f32 v72, v51, v50, 1.0
	v_pk_mul_f32 v[50:51], v[72:73], v[54:55] op_sel_hi:[0,1]
	v_pk_mul_f32 v[54:55], v[72:73], v[68:69] op_sel_hi:[0,1]
	ds_bpermute_b32 v68, v57, v65
	v_pk_mul_f32 v[52:53], v[72:73], v[52:53] op_sel_hi:[0,1]
	v_pk_mul_f32 v[52:53], v[2:3], v[52:53]
	v_pk_mul_f32 v[50:51], v[0:1], v[50:51]
	global_store_dwordx4 v[66:67], v[50:53], off offset:-3072
	s_nop 1
	v_pk_mul_f32 v[50:51], v[72:73], v[70:71] op_sel_hi:[0,1]
	v_pk_mul_f32 v[52:53], v[6:7], v[50:51]
	v_pk_mul_f32 v[50:51], v[4:5], v[54:55]
	s_waitcnt lgkmcnt(0)
	v_add_f32_e32 v54, v65, v68
	ds_bpermute_b32 v55, v58, v54
	global_store_dwordx4 v[66:67], v[50:53], off offset:-2048
	s_waitcnt lgkmcnt(0)
	v_add_f32_e32 v54, v54, v55
	ds_bpermute_b32 v55, v59, v54
	v_lshlrev_b32_e32 v50, 16, v48
	v_and_b32_e32 v51, 0xffff0000, v48
	v_lshlrev_b32_e32 v48, 16, v49
	v_and_b32_e32 v49, 0xffff0000, v49
	v_pk_mul_f32 v[52:53], v[72:73], v[50:51] op_sel_hi:[0,1]
	v_pk_mul_f32 v[48:49], v[72:73], v[48:49] op_sel_hi:[0,1]
	v_pk_mul_f32 v[50:51], v[10:11], v[48:49]
	v_pk_mul_f32 v[48:49], v[8:9], v[52:53]
	global_store_dwordx4 v[66:67], v[48:51], off offset:-1024
	s_waitcnt lgkmcnt(0)
; __device__ __forceinline__ float rs_of(float ss) { return 1.0f / sqrtf(ss * (1.f / 1024.f) + 1e-6f); }
; __device__ __forceinline__ void final_rows(const bf16_t* XB, float* out, const float* g, const float* SS, int gw, int NGW, int lane) {
;     ...
;     for (int m0 = 4 * gw; m0 < T; m0 += 4 * NGW) {
;         u32x2 w[4][4]; float tp[4];
; #pragma unroll
;         for (int q = 0; q < 4; ++q) { const u32x2* xr = (const u32x2*)(XB + (size_t)(m0 + q) * D) + lane;
; #pragma unroll
;             for (int j = 0; j < 4; ++j) w[q][j] = xr[64 * j];
;             tp[q] = (lane < 16) ? SS[(size_t)lane * T + m0 + q] : 0.f; }
; #pragma unroll
;         for (int q = 0; q < 4; ++q) { float t = tp[q]; t += __shfl_xor(t, 1); t += __shfl_xor(t, 2); t += __shfl_xor(t, 4); t += __shfl_xor(t, 8); const float r = rs_of(__shfl(t, 0));
;             f32x4* o = (f32x4*)(out + (size_t)(m0 + q) * D) + lane;
; #pragma unroll
;             for (int j = 0; j < 4; ++j) o[64 * j] = (f32x4){bf_lo(w[q][j].x), bf_hi(w[q][j].x), bf_lo(w[q][j].y), bf_hi(w[q][j].y)} * r * gv[j]; } }
	s_nop 0
	v_add_f32_e32 v49, v54, v55
	ds_bpermute_b32 v52, v60, v49
	v_lshlrev_b32_e32 v48, 16, v46
	v_and_b32_e32 v49, 0xffff0000, v46
	v_pk_mul_f32 v[50:51], v[72:73], v[48:49] op_sel_hi:[0,1]
	v_lshlrev_b32_e32 v46, 16, v47
	s_waitcnt lgkmcnt(0)
	v_fmamk_f32 v48, v52, 0x3a800000, v61
	v_mul_f32_e32 v49, 0x4f800000, v48
	v_cmp_gt_f32_e32 vcc, s5, v48
	v_and_b32_e32 v47, 0xffff0000, v47
	v_pk_mul_f32 v[46:47], v[72:73], v[46:47] op_sel_hi:[0,1]
	v_cndmask_b32_e32 v52, v48, v49, vcc
	v_sqrt_f32_e32 v53, v52
	v_pk_mul_f32 v[48:49], v[14:15], v[46:47]
	v_pk_mul_f32 v[46:47], v[12:13], v[50:51]
	v_add_u32_e32 v50, -1, v53
	v_fma_f32 v51, -v50, v53, v52
	v_cmp_ge_f32_e64 s[2:3], 0, v51
	v_add_u32_e32 v51, 1, v53
	s_nop 0
	v_cndmask_b32_e64 v50, v53, v50, s[2:3]
	v_fma_f32 v53, -v51, v53, v52
	v_cmp_lt_f32_e64 s[2:3], 0, v53
	s_nop 1
	v_cndmask_b32_e64 v50, v50, v51, s[2:3]
	v_mul_f32_e32 v51, 0x37800000, v50
	v_cndmask_b32_e32 v50, v50, v51, vcc
	v_cmp_class_f32_e32 vcc, v52, v62
	s_nop 1
	v_cndmask_b32_e32 v52, v50, v52, vcc
	v_div_scale_f32 v53, s[2:3], v52, v52, 1.0
	v_rcp_f32_e32 v54, v53
	v_add_co_u32_e32 v50, vcc, s14, v16
	s_nop 1
	v_addc_co_u32_e32 v51, vcc, -1, v17, vcc
	global_store_dwordx4 v[50:51], v[46:49], off offset:-4096
	s_nop 1
	v_fma_f32 v46, -v53, v54, 1.0
	v_fmac_f32_e32 v54, v46, v54
	v_div_scale_f32 v46, vcc, 1.0, v52, 1.0
	v_mul_f32_e32 v47, v46, v54
	v_fma_f32 v48, -v53, v47, v46
	v_fmac_f32_e32 v47, v48, v54
	v_fma_f32 v46, -v53, v47, v46
	v_div_fmas_f32 v46, v46, v54, v47
	v_div_fixup_f32 v48, v46, v52, 1.0
	v_lshlrev_b32_e32 v46, 16, v44
	v_and_b32_e32 v47, 0xffff0000, v44
	v_lshlrev_b32_e32 v44, 16, v45
	v_and_b32_e32 v45, 0xffff0000, v45
	v_pk_mul_f32 v[52:53], v[48:49], v[46:47] op_sel_hi:[0,1]
	v_pk_mul_f32 v[44:45], v[48:49], v[44:45] op_sel_hi:[0,1]
	ds_bpermute_b32 v49, v56, v64
	v_pk_mul_f32 v[46:47], v[2:3], v[44:45]
	v_pk_mul_f32 v[44:45], v[0:1], v[52:53]
	global_store_dwordx4 v[50:51], v[44:47], off offset:-3072
	s_nop 1
	v_lshlrev_b32_e32 v44, 16, v42
	v_and_b32_e32 v45, 0xffff0000, v42
	s_waitcnt lgkmcnt(0)
	v_pk_mul_f32 v[46:47], v[48:49], v[44:45] op_sel_hi:[0,1]
	v_add_f32_e32 v49, v64, v49
	ds_bpermute_b32 v52, v57, v49
	v_lshlrev_b32_e32 v42, 16, v43
	v_and_b32_e32 v43, 0xffff0000, v43
	v_pk_mul_f32 v[42:43], v[48:49], v[42:43] op_sel_hi:[0,1]
	v_pk_mul_f32 v[44:45], v[6:7], v[42:43]
	v_pk_mul_f32 v[42:43], v[4:5], v[46:47]
	global_store_dwordx4 v[50:51], v[42:45], off offset:-2048
	s_waitcnt lgkmcnt(0)
	s_nop 0
	v_add_f32_e32 v44, v49, v52
	ds_bpermute_b32 v45, v58, v44
	v_lshlrev_b32_e32 v42, 16, v40
	v_and_b32_e32 v43, 0xffff0000, v40
	v_lshlrev_b32_e32 v40, 16, v41
	v_and_b32_e32 v41, 0xffff0000, v41
	s_waitcnt lgkmcnt(0)
	v_add_f32_e32 v46, v44, v45
	ds_bpermute_b32 v47, v59, v46
	v_pk_mul_f32 v[44:45], v[48:49], v[42:43] op_sel_hi:[0,1]
	v_pk_mul_f32 v[40:41], v[48:49], v[40:41] op_sel_hi:[0,1]
	v_pk_mul_f32 v[42:43], v[10:11], v[40:41]
	v_pk_mul_f32 v[40:41], v[8:9], v[44:45]
	s_waitcnt lgkmcnt(0)
	v_add_f32_e32 v44, v46, v47
	ds_bpermute_b32 v44, v60, v44
	global_store_dwordx4 v[50:51], v[40:43], off offset:-1024
	s_nop 1
	v_lshlrev_b32_e32 v40, 16, v38
	s_waitcnt lgkmcnt(0)
	v_fmamk_f32 v42, v44, 0x3a800000, v61
	v_mul_f32_e32 v43, 0x4f800000, v42
	v_cmp_gt_f32_e32 vcc, s5, v42
	v_and_b32_e32 v41, 0xffff0000, v38
	v_lshlrev_b32_e32 v38, 16, v39
	v_cndmask_b32_e32 v44, v42, v43, vcc
	v_sqrt_f32_e32 v45, v44
	v_pk_mul_f32 v[42:43], v[48:49], v[40:41] op_sel_hi:[0,1]
	v_and_b32_e32 v39, 0xffff0000, v39
	v_pk_mul_f32 v[38:39], v[48:49], v[38:39] op_sel_hi:[0,1]
	v_add_u32_e32 v40, -1, v45
	v_fma_f32 v41, -v40, v45, v44
	v_cmp_ge_f32_e64 s[2:3], 0, v41
	v_add_u32_e32 v41, 1, v45
	s_nop 0
	v_cndmask_b32_e64 v40, v45, v40, s[2:3]
	v_fma_f32 v45, -v41, v45, v44
	v_cmp_lt_f32_e64 s[2:3], 0, v45
	s_nop 1
	v_cndmask_b32_e64 v40, v40, v41, s[2:3]
	v_mul_f32_e32 v41, 0x37800000, v40
	v_cndmask_b32_e32 v40, v40, v41, vcc
	v_cmp_class_f32_e32 vcc, v44, v62
	s_nop 1
	v_cndmask_b32_e32 v44, v40, v44, vcc
	v_div_scale_f32 v45, s[2:3], v44, v44, 1.0
	v_rcp_f32_e32 v46, v45
	v_pk_mul_f32 v[40:41], v[14:15], v[38:39]
	v_pk_mul_f32 v[38:39], v[12:13], v[42:43]
	global_store_dwordx4 v[50:51], v[38:41], off
	s_nop 1
	v_fma_f32 v38, -v45, v46, 1.0
	v_fmac_f32_e32 v46, v38, v46
	v_div_scale_f32 v38, vcc, 1.0, v44, 1.0
	v_mul_f32_e32 v39, v38, v46
	v_fma_f32 v40, -v45, v39, v38
	v_fmac_f32_e32 v39, v40, v46
	v_fma_f32 v38, -v45, v39, v38
	v_div_fmas_f32 v38, v38, v46, v39
	v_div_fixup_f32 v40, v38, v44, 1.0
	v_lshlrev_b32_e32 v38, 16, v36
	v_and_b32_e32 v39, 0xffff0000, v36
	v_lshlrev_b32_e32 v36, 16, v37
	v_and_b32_e32 v37, 0xffff0000, v37
	v_pk_mul_f32 v[42:43], v[40:41], v[38:39] op_sel_hi:[0,1]
	v_pk_mul_f32 v[36:37], v[40:41], v[36:37] op_sel_hi:[0,1]
	ds_bpermute_b32 v41, v56, v63
	v_pk_mul_f32 v[38:39], v[2:3], v[36:37]
	v_pk_mul_f32 v[36:37], v[0:1], v[42:43]
	v_add_co_u32_e32 v42, vcc, s15, v16
	s_nop 1
	v_addc_co_u32_e32 v43, vcc, -1, v17, vcc
	global_store_dwordx4 v[42:43], v[36:39], off offset:-3072
	s_nop 1
	v_lshlrev_b32_e32 v36, 16, v34
	v_and_b32_e32 v37, 0xffff0000, v34
	s_waitcnt lgkmcnt(0)
; __device__ __forceinline__ float rs_of(float ss) { return 1.0f / sqrtf(ss * (1.f / 1024.f) + 1e-6f); }
; __device__ __forceinline__ void final_rows(const bf16_t* XB, float* out, const float* g, const float* SS, int gw, int NGW, int lane) {
;     ...
;     for (int m0 = 4 * gw; m0 < T; m0 += 4 * NGW) {
;         u32x2 w[4][4]; float tp[4];
; #pragma unroll
;         for (int q = 0; q < 4; ++q) { const u32x2* xr = (const u32x2*)(XB + (size_t)(m0 + q) * D) + lane;
; #pragma unroll
;             for (int j = 0; j < 4; ++j) w[q][j] = xr[64 * j];
;             tp[q] = (lane < 16) ? SS[(size_t)lane * T + m0 + q] : 0.f; }
; #pragma unroll
;         for (int q = 0; q < 4; ++q) { float t = tp[q]; t += __shfl_xor(t, 1); t += __shfl_xor(t, 2); t += __shfl_xor(t, 4); t += __shfl_xor(t, 8); const float r = rs_of(__shfl(t, 0));
;             f32x4* o = (f32x4*)(out + (size_t)(m0 + q) * D) + lane;
; #pragma unroll
;             for (int j = 0; j < 4; ++j) o[64 * j] = (f32x4){bf_lo(w[q][j].x), bf_hi(w[q][j].x), bf_lo(w[q][j].y), bf_hi(w[q][j].y)} * r * gv[j]; } }
	v_pk_mul_f32 v[38:39], v[40:41], v[36:37] op_sel_hi:[0,1]
	v_add_f32_e32 v41, v63, v41
	ds_bpermute_b32 v44, v57, v41
	v_lshlrev_b32_e32 v34, 16, v35
	v_and_b32_e32 v35, 0xffff0000, v35
	v_pk_mul_f32 v[34:35], v[40:41], v[34:35] op_sel_hi:[0,1]
	v_pk_mul_f32 v[36:37], v[6:7], v[34:35]
	v_pk_mul_f32 v[34:35], v[4:5], v[38:39]
	global_store_dwordx4 v[42:43], v[34:37], off offset:-2048
	s_waitcnt lgkmcnt(0)
	s_nop 0
	v_add_f32_e32 v36, v41, v44
	ds_bpermute_b32 v37, v58, v36
	v_lshlrev_b32_e32 v34, 16, v32
	v_and_b32_e32 v35, 0xffff0000, v32
	v_lshlrev_b32_e32 v32, 16, v33
	v_and_b32_e32 v33, 0xffff0000, v33
	s_waitcnt lgkmcnt(0)
	v_add_f32_e32 v38, v36, v37
	ds_bpermute_b32 v39, v59, v38
	v_pk_mul_f32 v[36:37], v[40:41], v[34:35] op_sel_hi:[0,1]
	v_pk_mul_f32 v[32:33], v[40:41], v[32:33] op_sel_hi:[0,1]
	v_pk_mul_f32 v[34:35], v[10:11], v[32:33]
	v_pk_mul_f32 v[32:33], v[8:9], v[36:37]
	s_waitcnt lgkmcnt(0)
	v_add_f32_e32 v36, v38, v39
	ds_bpermute_b32 v36, v60, v36
	global_store_dwordx4 v[42:43], v[32:35], off offset:-1024
	s_nop 1
	v_lshlrev_b32_e32 v32, 16, v30
	s_waitcnt lgkmcnt(0)
	v_fmamk_f32 v34, v36, 0x3a800000, v61
	v_mul_f32_e32 v35, 0x4f800000, v34
	v_cmp_gt_f32_e32 vcc, s5, v34
	v_and_b32_e32 v33, 0xffff0000, v30
	v_lshlrev_b32_e32 v30, 16, v31
	v_cndmask_b32_e32 v36, v34, v35, vcc
	v_sqrt_f32_e32 v37, v36
	v_pk_mul_f32 v[34:35], v[40:41], v[32:33] op_sel_hi:[0,1]
	v_and_b32_e32 v31, 0xffff0000, v31
	v_pk_mul_f32 v[30:31], v[40:41], v[30:31] op_sel_hi:[0,1]
	v_add_u32_e32 v32, -1, v37
	v_fma_f32 v33, -v32, v37, v36
	v_cmp_ge_f32_e64 s[2:3], 0, v33
	v_add_u32_e32 v33, 1, v37
	s_nop 0
	v_cndmask_b32_e64 v32, v37, v32, s[2:3]
	v_fma_f32 v37, -v33, v37, v36
	v_cmp_lt_f32_e64 s[2:3], 0, v37
	s_nop 1
	v_cndmask_b32_e64 v32, v32, v33, s[2:3]
	v_mul_f32_e32 v33, 0x37800000, v32
	v_cndmask_b32_e32 v32, v32, v33, vcc
	v_cmp_class_f32_e32 vcc, v36, v62
	s_nop 1
	v_cndmask_b32_e32 v36, v32, v36, vcc
	v_div_scale_f32 v37, s[2:3], v36, v36, 1.0
	v_rcp_f32_e32 v38, v37
	v_pk_mul_f32 v[32:33], v[14:15], v[30:31]
	v_pk_mul_f32 v[30:31], v[12:13], v[34:35]
	global_store_dwordx4 v[16:17], v[30:33], off offset:-4096
	s_nop 1
	v_fma_f32 v30, -v37, v38, 1.0
	v_fmac_f32_e32 v38, v30, v38
	v_div_scale_f32 v30, vcc, 1.0, v36, 1.0
	v_mul_f32_e32 v31, v30, v38
	v_fma_f32 v32, -v37, v31, v30
	v_fmac_f32_e32 v31, v32, v38
	v_fma_f32 v30, -v37, v31, v30
	v_div_fmas_f32 v30, v30, v38, v31
	v_div_fixup_f32 v32, v30, v36, 1.0
	v_lshlrev_b32_e32 v30, 16, v28
	v_and_b32_e32 v31, 0xffff0000, v28
	v_lshlrev_b32_e32 v28, 16, v29
	v_and_b32_e32 v29, 0xffff0000, v29
	v_pk_mul_f32 v[34:35], v[32:33], v[30:31] op_sel_hi:[0,1]
	v_pk_mul_f32 v[28:29], v[32:33], v[28:29] op_sel_hi:[0,1]
	v_pk_mul_f32 v[30:31], v[2:3], v[28:29]
	v_pk_mul_f32 v[28:29], v[0:1], v[34:35]
	global_store_dwordx4 v[16:17], v[28:31], off offset:-3072
	s_nop 1
	v_lshlrev_b32_e32 v28, 16, v26
	v_and_b32_e32 v29, 0xffff0000, v26
	v_lshlrev_b32_e32 v26, 16, v27
	v_and_b32_e32 v27, 0xffff0000, v27
	v_pk_mul_f32 v[30:31], v[32:33], v[28:29] op_sel_hi:[0,1]
	v_pk_mul_f32 v[26:27], v[32:33], v[26:27] op_sel_hi:[0,1]
	v_pk_mul_f32 v[28:29], v[6:7], v[26:27]
	v_pk_mul_f32 v[26:27], v[4:5], v[30:31]
	global_store_dwordx4 v[16:17], v[26:29], off offset:-2048
	s_nop 1
	v_lshlrev_b32_e32 v26, 16, v24
	v_and_b32_e32 v27, 0xffff0000, v24
	v_lshlrev_b32_e32 v24, 16, v25
	v_and_b32_e32 v25, 0xffff0000, v25
	v_pk_mul_f32 v[28:29], v[32:33], v[26:27] op_sel_hi:[0,1]
	v_pk_mul_f32 v[24:25], v[32:33], v[24:25] op_sel_hi:[0,1]
	v_pk_mul_f32 v[26:27], v[10:11], v[24:25]
	v_pk_mul_f32 v[24:25], v[8:9], v[28:29]
	global_store_dwordx4 v[16:17], v[24:27], off offset:-1024
	s_nop 1
	v_lshlrev_b32_e32 v24, 16, v22
	v_and_b32_e32 v25, 0xffff0000, v22
	v_lshlrev_b32_e32 v22, 16, v23
	v_and_b32_e32 v23, 0xffff0000, v23
	v_pk_mul_f32 v[26:27], v[32:33], v[24:25] op_sel_hi:[0,1]
	v_pk_mul_f32 v[22:23], v[32:33], v[22:23] op_sel_hi:[0,1]
	v_pk_mul_f32 v[24:25], v[14:15], v[22:23]
	v_pk_mul_f32 v[22:23], v[12:13], v[26:27]
	global_store_dwordx4 v[16:17], v[22:25], off
	v_lshl_add_u64 v[16:17], v[16:17], 0, s[8:9]
	s_cbranch_scc0 .LBB0_1914
